# baseline (speedup 1.0000x reference)
; __device__ __forceinline__ unsigned pk2(float lo, float hi) { const f32x2_t v = {lo, hi}; return __builtin_bit_cast(unsigned, __builtin_convertvector(v, bf16x2_t)); }
; template <int A0, int A1, int B0, int B1, bool LOC> ...
;     ...
;     float ps = 0.f;
; #pragma unroll
;     for (int i = 0; i < 16; ++i) { if (i >= A0 && i < A1) { s0[i] = __builtin_amdgcn_exp2f(s0[i] - mn); ps += s0[i]; } else s0[i] = 0.f; }
; #pragma unroll
;     for (int i = 0; i < 16; ++i) { if (i >= B0 && i < B1) { s1v[i] = __builtin_amdgcn_exp2f(s1v[i] - mn); ps += s1v[i]; } else s1v[i] = 0.f; }
;     lsum += ps;
; #pragma unroll
;     for (int kk = 0; kk < 4; ++kk) {
;         const int o = 8 * (kk & 1); const bool live = (kk < 2) ? (o < A1 && o + 8 > A0) : (o < B1 && o + 8 > B0);
;         if (!live) continue;
;         u32x4 pw;
;         if (kk < 2) { pw.x = pk2(s0[o], s0[o + 1]); pw.y = pk2(s0[o + 2], s0[o + 3]); pw.z = pk2(s0[o + 4], s0[o + 5]); pw.w = pk2(s0[o + 6], s0[o + 7]); }
;         else { pw.x = pk2(s1v[o], s1v[o + 1]); pw.y = pk2(s1v[o + 2], s1v[o + 3]); pw.z = pk2(s1v[o + 4], s1v[o + 5]); pw.w = pk2(s1v[o + 6], s1v[o + 7]); }
;         const bf16x8 pf = __builtin_bit_cast(bf16x8, pw);
;         const bf16x8 v0 = tr2(vbuf + kk * 2048 + vro + ((0 ^ vsw) * 64), 1024), v1 = tr2(vbuf + kk * 2048 + vro + ((1 ^ vsw) * 64), 1024);
;         o0 = __builtin_amdgcn_mfma_f32_32x32x16_bf16(v0, pf, o0, 0, 0, 0);
;         o1 = __builtin_amdgcn_mfma_f32_32x32x16_bf16(v1, pf, o1, 0, 0, 0);
;     }
.LBB0_499:
	v_add_u32_e32 v0, v183, v184
	v_add_u32_e32 v1, v183, v185
	ds_read_b64_tr_b16 v[72:73], v0 offset:32768
	ds_read_b64_tr_b16 v[74:75], v0 offset:33792
	ds_read_b64_tr_b16 v[76:77], v1 offset:32768
	ds_read_b64_tr_b16 v[78:79], v1 offset:33792
	v_pk_add_f32 v[52:53], v[52:53], v[194:195] op_sel:[0,1] op_sel_hi:[1,1] neg_lo:[0,1] neg_hi:[0,1]
	v_pk_add_f32 v[54:55], v[54:55], v[194:195] op_sel:[0,1] op_sel_hi:[1,1] neg_lo:[0,1] neg_hi:[0,1]
	v_pk_add_f32 v[56:57], v[56:57], v[194:195] op_sel:[0,1] op_sel_hi:[1,1] neg_lo:[0,1] neg_hi:[0,1]
	v_pk_add_f32 v[58:59], v[58:59], v[194:195] op_sel:[0,1] op_sel_hi:[1,1] neg_lo:[0,1] neg_hi:[0,1]
	v_pk_add_f32 v[60:61], v[60:61], v[194:195] op_sel:[0,1] op_sel_hi:[1,1] neg_lo:[0,1] neg_hi:[0,1]
	v_pk_add_f32 v[62:63], v[62:63], v[194:195] op_sel:[0,1] op_sel_hi:[1,1] neg_lo:[0,1] neg_hi:[0,1]
	v_pk_add_f32 v[64:65], v[64:65], v[194:195] op_sel:[0,1] op_sel_hi:[1,1] neg_lo:[0,1] neg_hi:[0,1]
	v_pk_add_f32 v[66:67], v[66:67], v[194:195] op_sel:[0,1] op_sel_hi:[1,1] neg_lo:[0,1] neg_hi:[0,1]
	v_pk_add_f32 v[36:37], v[36:37], v[194:195] op_sel:[0,1] op_sel_hi:[1,1] neg_lo:[0,1] neg_hi:[0,1]
	v_pk_add_f32 v[38:39], v[38:39], v[194:195] op_sel:[0,1] op_sel_hi:[1,1] neg_lo:[0,1] neg_hi:[0,1]
	v_pk_add_f32 v[40:41], v[40:41], v[194:195] op_sel:[0,1] op_sel_hi:[1,1] neg_lo:[0,1] neg_hi:[0,1]
	v_pk_add_f32 v[42:43], v[42:43], v[194:195] op_sel:[0,1] op_sel_hi:[1,1] neg_lo:[0,1] neg_hi:[0,1]
	v_pk_add_f32 v[44:45], v[44:45], v[194:195] op_sel:[0,1] op_sel_hi:[1,1] neg_lo:[0,1] neg_hi:[0,1]
	v_pk_add_f32 v[46:47], v[46:47], v[194:195] op_sel:[0,1] op_sel_hi:[1,1] neg_lo:[0,1] neg_hi:[0,1]
	v_pk_add_f32 v[48:49], v[48:49], v[194:195] op_sel:[0,1] op_sel_hi:[1,1] neg_lo:[0,1] neg_hi:[0,1]
	v_pk_add_f32 v[50:51], v[50:51], v[194:195] op_sel:[0,1] op_sel_hi:[1,1] neg_lo:[0,1] neg_hi:[0,1]
	v_exp_f32_e32 v52, v52
	v_exp_f32_e32 v53, v53
	v_exp_f32_e32 v54, v54
	v_exp_f32_e32 v55, v55
	v_exp_f32_e32 v56, v56
	v_exp_f32_e32 v57, v57
	v_pk_add_f32 v[80:81], v[52:53], v[54:55]
	v_exp_f32_e32 v58, v58
	v_exp_f32_e32 v59, v59
	v_pk_add_f32 v[80:81], v[80:81], v[56:57]
	v_exp_f32_e32 v60, v60
	v_exp_f32_e32 v61, v61
	v_pk_add_f32 v[80:81], v[80:81], v[58:59]
	v_exp_f32_e32 v62, v62
	v_exp_f32_e32 v63, v63
	v_pk_add_f32 v[80:81], v[80:81], v[60:61]
	v_exp_f32_e32 v64, v64
	v_exp_f32_e32 v65, v65
	v_pk_add_f32 v[80:81], v[80:81], v[62:63]
	v_exp_f32_e32 v66, v66
	v_exp_f32_e32 v67, v67
	v_pk_add_f32 v[80:81], v[80:81], v[64:65]
	v_exp_f32_e32 v36, v36
	v_exp_f32_e32 v37, v37
	v_pk_add_f32 v[80:81], v[80:81], v[66:67]
	v_exp_f32_e32 v38, v38
	v_exp_f32_e32 v39, v39
	v_pk_add_f32 v[80:81], v[80:81], v[36:37]
	v_exp_f32_e32 v40, v40
	v_exp_f32_e32 v41, v41
	v_pk_add_f32 v[80:81], v[80:81], v[38:39]
	v_exp_f32_e32 v42, v42
	v_exp_f32_e32 v43, v43
	v_pk_add_f32 v[80:81], v[80:81], v[40:41]
	v_exp_f32_e32 v44, v44
	v_exp_f32_e32 v45, v45
	v_pk_add_f32 v[80:81], v[80:81], v[42:43]
	v_exp_f32_e32 v46, v46
	v_exp_f32_e32 v47, v47
	v_pk_add_f32 v[80:81], v[80:81], v[44:45]
	v_exp_f32_e32 v48, v48
	v_exp_f32_e32 v49, v49
	v_pk_add_f32 v[80:81], v[80:81], v[46:47]
	v_exp_f32_e32 v50, v50
	v_exp_f32_e32 v51, v51
	v_pk_add_f32 v[80:81], v[80:81], v[48:49]
	s_nop 1
	v_pk_add_f32 v[80:81], v[80:81], v[50:51]
	s_nop 0
	v_add_f32_e32 v3, v80, v81
	v_add_f32_e32 v196, v3, v141
	ds_read_b64_tr_b16 v[84:85], v0 offset:34816
	ds_read_b64_tr_b16 v[86:87], v0 offset:35840
	ds_read_b64_tr_b16 v[88:89], v1 offset:34816
	ds_read_b64_tr_b16 v[90:91], v1 offset:35840
	v_cvt_pk_bf16_f32 v68, v52, v53
	v_cvt_pk_bf16_f32 v69, v54, v55
	v_cvt_pk_bf16_f32 v70, v56, v57
	v_cvt_pk_bf16_f32 v71, v58, v59
	s_waitcnt lgkmcnt(4)
	s_nop 1
	v_mfma_f32_32x32x16_bf16 v[20:35], v[72:75], v[68:71], v[20:35]
	v_mfma_f32_32x32x16_bf16 v[4:19], v[76:79], v[68:71], v[4:19]
	ds_read_b64_tr_b16 v[72:73], v0 offset:36864
	ds_read_b64_tr_b16 v[74:75], v0 offset:37888
	ds_read_b64_tr_b16 v[76:77], v1 offset:36864
	ds_read_b64_tr_b16 v[78:79], v1 offset:37888
	v_cvt_pk_bf16_f32 v92, v60, v61
	v_cvt_pk_bf16_f32 v93, v62, v63
	v_cvt_pk_bf16_f32 v94, v64, v65
	v_cvt_pk_bf16_f32 v95, v66, v67
	s_waitcnt lgkmcnt(4)
	s_nop 1
	v_mfma_f32_32x32x16_bf16 v[20:35], v[84:87], v[92:95], v[20:35]
	v_mfma_f32_32x32x16_bf16 v[4:19], v[88:91], v[92:95], v[4:19]
	ds_read_b64_tr_b16 v[84:85], v0 offset:38912
	ds_read_b64_tr_b16 v[86:87], v0 offset:39936
	ds_read_b64_tr_b16 v[88:89], v1 offset:38912
	ds_read_b64_tr_b16 v[90:91], v1 offset:39936
	v_cvt_pk_bf16_f32 v68, v36, v37
	v_cvt_pk_bf16_f32 v69, v38, v39
	v_cvt_pk_bf16_f32 v70, v40, v41
	v_cvt_pk_bf16_f32 v71, v42, v43
	s_waitcnt lgkmcnt(4)
	s_nop 1
	v_mfma_f32_32x32x16_bf16 v[20:35], v[72:75], v[68:71], v[20:35]
	v_mfma_f32_32x32x16_bf16 v[4:19], v[76:79], v[68:71], v[4:19]
	v_cvt_pk_bf16_f32 v92, v44, v45
	v_cvt_pk_bf16_f32 v93, v46, v47
	v_cvt_pk_bf16_f32 v94, v48, v49
	v_cvt_pk_bf16_f32 v95, v50, v51
	s_waitcnt lgkmcnt(0)
	s_nop 1
	v_mfma_f32_32x32x16_bf16 v[20:35], v[84:87], v[92:95], v[20:35]
	v_mfma_f32_32x32x16_bf16 v[4:19], v[88:91], v[92:95], v[4:19]

; __device__ __forceinline__ unsigned pk2(float lo, float hi) { const f32x2_t v = {lo, hi}; return __builtin_bit_cast(unsigned, __builtin_convertvector(v, bf16x2_t)); }
; template <int A0, int A1, int B0, int B1, bool LOC> ...
;     ...
;     float ps = 0.f;
; #pragma unroll
;     for (int i = 0; i < 16; ++i) { if (i >= A0 && i < A1) { s0[i] = __builtin_amdgcn_exp2f(s0[i] - mn); ps += s0[i]; } else s0[i] = 0.f; }
; #pragma unroll
;     for (int i = 0; i < 16; ++i) { if (i >= B0 && i < B1) { s1v[i] = __builtin_amdgcn_exp2f(s1v[i] - mn); ps += s1v[i]; } else s1v[i] = 0.f; }
;     lsum += ps;
; #pragma unroll
;     for (int kk = 0; kk < 4; ++kk) {
;         const int o = 8 * (kk & 1); const bool live = (kk < 2) ? (o < A1 && o + 8 > A0) : (o < B1 && o + 8 > B0);
;         if (!live) continue;
;         u32x4 pw;
;         if (kk < 2) { pw.x = pk2(s0[o], s0[o + 1]); pw.y = pk2(s0[o + 2], s0[o + 3]); pw.z = pk2(s0[o + 4], s0[o + 5]); pw.w = pk2(s0[o + 6], s0[o + 7]); }
;         else { pw.x = pk2(s1v[o], s1v[o + 1]); pw.y = pk2(s1v[o + 2], s1v[o + 3]); pw.z = pk2(s1v[o + 4], s1v[o + 5]); pw.w = pk2(s1v[o + 6], s1v[o + 7]); }
;         const bf16x8 pf = __builtin_bit_cast(bf16x8, pw);
;         const bf16x8 v0 = tr2(vbuf + kk * 2048 + vro + ((0 ^ vsw) * 64), 1024), v1 = tr2(vbuf + kk * 2048 + vro + ((1 ^ vsw) * 64), 1024);
;         o0 = __builtin_amdgcn_mfma_f32_32x32x16_bf16(v0, pf, o0, 0, 0, 0);
;         o1 = __builtin_amdgcn_mfma_f32_32x32x16_bf16(v1, pf, o1, 0, 0, 0);
;     }
.LBB0_523:
	v_add_u32_e32 v0, v183, v184
	v_add_u32_e32 v1, v183, v185
	ds_read_b64_tr_b16 v[72:73], v0 offset:40960
	ds_read_b64_tr_b16 v[74:75], v0 offset:41984
	ds_read_b64_tr_b16 v[76:77], v1 offset:40960
	ds_read_b64_tr_b16 v[78:79], v1 offset:41984
	v_pk_add_f32 v[52:53], v[52:53], v[194:195] op_sel:[0,1] op_sel_hi:[1,1] neg_lo:[0,1] neg_hi:[0,1]
	v_pk_add_f32 v[54:55], v[54:55], v[194:195] op_sel:[0,1] op_sel_hi:[1,1] neg_lo:[0,1] neg_hi:[0,1]
	v_pk_add_f32 v[56:57], v[56:57], v[194:195] op_sel:[0,1] op_sel_hi:[1,1] neg_lo:[0,1] neg_hi:[0,1]
	v_pk_add_f32 v[58:59], v[58:59], v[194:195] op_sel:[0,1] op_sel_hi:[1,1] neg_lo:[0,1] neg_hi:[0,1]
	v_pk_add_f32 v[60:61], v[60:61], v[194:195] op_sel:[0,1] op_sel_hi:[1,1] neg_lo:[0,1] neg_hi:[0,1]
	v_pk_add_f32 v[62:63], v[62:63], v[194:195] op_sel:[0,1] op_sel_hi:[1,1] neg_lo:[0,1] neg_hi:[0,1]
	v_pk_add_f32 v[64:65], v[64:65], v[194:195] op_sel:[0,1] op_sel_hi:[1,1] neg_lo:[0,1] neg_hi:[0,1]
	v_pk_add_f32 v[66:67], v[66:67], v[194:195] op_sel:[0,1] op_sel_hi:[1,1] neg_lo:[0,1] neg_hi:[0,1]
	v_pk_add_f32 v[36:37], v[36:37], v[194:195] op_sel:[0,1] op_sel_hi:[1,1] neg_lo:[0,1] neg_hi:[0,1]
	v_pk_add_f32 v[38:39], v[38:39], v[194:195] op_sel:[0,1] op_sel_hi:[1,1] neg_lo:[0,1] neg_hi:[0,1]
	v_pk_add_f32 v[40:41], v[40:41], v[194:195] op_sel:[0,1] op_sel_hi:[1,1] neg_lo:[0,1] neg_hi:[0,1]
	v_pk_add_f32 v[42:43], v[42:43], v[194:195] op_sel:[0,1] op_sel_hi:[1,1] neg_lo:[0,1] neg_hi:[0,1]
	v_pk_add_f32 v[44:45], v[44:45], v[194:195] op_sel:[0,1] op_sel_hi:[1,1] neg_lo:[0,1] neg_hi:[0,1]
	v_pk_add_f32 v[46:47], v[46:47], v[194:195] op_sel:[0,1] op_sel_hi:[1,1] neg_lo:[0,1] neg_hi:[0,1]
	v_pk_add_f32 v[48:49], v[48:49], v[194:195] op_sel:[0,1] op_sel_hi:[1,1] neg_lo:[0,1] neg_hi:[0,1]
	v_pk_add_f32 v[50:51], v[50:51], v[194:195] op_sel:[0,1] op_sel_hi:[1,1] neg_lo:[0,1] neg_hi:[0,1]
	v_exp_f32_e32 v52, v52
	v_exp_f32_e32 v53, v53
	v_exp_f32_e32 v54, v54
	v_exp_f32_e32 v55, v55
	v_exp_f32_e32 v56, v56
	v_exp_f32_e32 v57, v57
	v_pk_add_f32 v[80:81], v[52:53], v[54:55]
	v_exp_f32_e32 v58, v58
	v_exp_f32_e32 v59, v59
	v_pk_add_f32 v[80:81], v[80:81], v[56:57]
	v_exp_f32_e32 v60, v60
	v_exp_f32_e32 v61, v61
	v_pk_add_f32 v[80:81], v[80:81], v[58:59]
	v_exp_f32_e32 v62, v62
	v_exp_f32_e32 v63, v63
	v_pk_add_f32 v[80:81], v[80:81], v[60:61]
	v_exp_f32_e32 v64, v64
	v_exp_f32_e32 v65, v65
	v_pk_add_f32 v[80:81], v[80:81], v[62:63]
	v_exp_f32_e32 v66, v66
	v_exp_f32_e32 v67, v67
	v_pk_add_f32 v[80:81], v[80:81], v[64:65]
	v_exp_f32_e32 v36, v36
	v_exp_f32_e32 v37, v37
	v_pk_add_f32 v[80:81], v[80:81], v[66:67]
	v_exp_f32_e32 v38, v38
	v_exp_f32_e32 v39, v39
	v_pk_add_f32 v[80:81], v[80:81], v[36:37]
	v_exp_f32_e32 v40, v40
	v_exp_f32_e32 v41, v41
	v_pk_add_f32 v[80:81], v[80:81], v[38:39]
	v_exp_f32_e32 v42, v42
	v_exp_f32_e32 v43, v43
	v_pk_add_f32 v[80:81], v[80:81], v[40:41]
	v_exp_f32_e32 v44, v44
	v_exp_f32_e32 v45, v45
	v_pk_add_f32 v[80:81], v[80:81], v[42:43]
	v_exp_f32_e32 v46, v46
	v_exp_f32_e32 v47, v47
	v_pk_add_f32 v[80:81], v[80:81], v[44:45]
	v_exp_f32_e32 v48, v48
	v_exp_f32_e32 v49, v49
	v_pk_add_f32 v[80:81], v[80:81], v[46:47]
	v_exp_f32_e32 v50, v50
	v_exp_f32_e32 v51, v51
	v_pk_add_f32 v[80:81], v[80:81], v[48:49]
	s_nop 1
	v_pk_add_f32 v[80:81], v[80:81], v[50:51]
	s_nop 0
	v_add_f32_e32 v3, v80, v81
	v_add_f32_e32 v196, v3, v141
	ds_read_b64_tr_b16 v[84:85], v0 offset:43008
	ds_read_b64_tr_b16 v[86:87], v0 offset:44032
	ds_read_b64_tr_b16 v[88:89], v1 offset:43008
	ds_read_b64_tr_b16 v[90:91], v1 offset:44032
	v_cvt_pk_bf16_f32 v68, v52, v53
	v_cvt_pk_bf16_f32 v69, v54, v55
	v_cvt_pk_bf16_f32 v70, v56, v57
	v_cvt_pk_bf16_f32 v71, v58, v59
	s_waitcnt lgkmcnt(4)
	s_nop 1
	v_mfma_f32_32x32x16_bf16 v[20:35], v[72:75], v[68:71], v[20:35]
	v_mfma_f32_32x32x16_bf16 v[4:19], v[76:79], v[68:71], v[4:19]
	ds_read_b64_tr_b16 v[72:73], v0 offset:45056
	ds_read_b64_tr_b16 v[74:75], v0 offset:46080
	ds_read_b64_tr_b16 v[76:77], v1 offset:45056
	ds_read_b64_tr_b16 v[78:79], v1 offset:46080
	v_cvt_pk_bf16_f32 v92, v60, v61
	v_cvt_pk_bf16_f32 v93, v62, v63
	v_cvt_pk_bf16_f32 v94, v64, v65
	v_cvt_pk_bf16_f32 v95, v66, v67
	s_waitcnt lgkmcnt(4)
	s_nop 1
	v_mfma_f32_32x32x16_bf16 v[20:35], v[84:87], v[92:95], v[20:35]
	v_mfma_f32_32x32x16_bf16 v[4:19], v[88:91], v[92:95], v[4:19]
	ds_read_b64_tr_b16 v[84:85], v0 offset:47104
	ds_read_b64_tr_b16 v[86:87], v0 offset:48128
	ds_read_b64_tr_b16 v[88:89], v1 offset:47104
	ds_read_b64_tr_b16 v[90:91], v1 offset:48128
	v_cvt_pk_bf16_f32 v68, v36, v37
	v_cvt_pk_bf16_f32 v69, v38, v39
	v_cvt_pk_bf16_f32 v70, v40, v41
	v_cvt_pk_bf16_f32 v71, v42, v43
	s_waitcnt lgkmcnt(4)
	s_nop 1
	v_mfma_f32_32x32x16_bf16 v[20:35], v[72:75], v[68:71], v[20:35]
	v_mfma_f32_32x32x16_bf16 v[4:19], v[76:79], v[68:71], v[4:19]
	v_cvt_pk_bf16_f32 v92, v44, v45
	v_cvt_pk_bf16_f32 v93, v46, v47
	v_cvt_pk_bf16_f32 v94, v48, v49
	v_cvt_pk_bf16_f32 v95, v50, v51
	s_waitcnt lgkmcnt(0)
	s_nop 1
	v_mfma_f32_32x32x16_bf16 v[20:35], v[84:87], v[92:95], v[20:35]
	v_mfma_f32_32x32x16_bf16 v[4:19], v[88:91], v[92:95], v[4:19]
